# MLA: rescale bookkeeping (cross-half exchange, exponent shift, alpha) only on a wave-uniform rare path when a half-row tile sum exceeds 2^13; lsum rescale folded into the rare rescale block (verified
# baseline (speedup 1.0000x reference)
; #define M2_STORE(S, buf) { M2_SK(0, S##k0, buf) M2_SK(1, S##k1, buf) M2_SK(2, S##k2, buf) M2_SV(0, S##v0, buf) M2_SV(1, S##v1, buf) }
; DI void flash_mla2(const bf16_t* __restrict__ Qp, const bf16_t* __restrict__ Kp, const bf16_t* __restrict__ Vtp,
;                    bf16_t* __restrict__ Op, char* smem, float& ssq) {
;     ...
;     for (int kt = 0; kt < NKT; kt += 2) {
;         M2_STORE(a, 0);
;         __syncthreads();
;         M2_LOAD(a, min(kt + 2, NKT - 1));
;         M2_COMPUTE(0);
;         M2_STORE(b, 1);
.LBB0_184:
	s_add_i32 s35, s35, 2
	s_min_u32 s36, s35, 0x7c
	s_add_i32 s41, s36, 3
	s_mul_i32 s36, s41, 0x3000
	s_add_u32 s36, s16, s36
	s_addc_u32 s37, s17, 0
	s_waitcnt lgkmcnt(0)
	s_barrier
	s_waitcnt vmcnt(9)
	ds_write_b128 v144, v[112:115] offset:13312
	s_waitcnt vmcnt(8)
	ds_write_b128 v145, v[116:119] offset:13312
	s_waitcnt vmcnt(6)
	ds_write_b128 v146, v[124:127] offset:13312
	ds_write_b128 v147, v[120:123] offset:35840
	s_waitcnt vmcnt(5)
	ds_write_b128 v148, v[128:131] offset:35840
	global_load_dwordx4 v[112:115], v136, s[36:37]
	global_load_dwordx4 v[116:119], v137, s[36:37] offset:-4096
	global_load_dwordx4 v[124:127], v137, s[36:37]
	s_lshl_b32 s36, s41, 13
	s_add_u32 s36, s18, s36
	s_addc_u32 s37, s19, 0
	s_add_u32 s36, s36, 0x800
	s_addc_u32 s37, s37, 0
	global_load_dwordx4 v[120:123], v151, s[36:37] offset:-2048
	global_load_dwordx4 v[128:131], v151, s[36:37] offset:2048
	v_cmp_neq_f32_e32 vcc, 1.0, v138
	s_cbranch_vccz .Lmla_c0
	v_pk_mul_f32 v[32:33], v[138:139], v[32:33] op_sel_hi:[0,1]
	v_pk_mul_f32 v[30:31], v[138:139], v[30:31] op_sel_hi:[0,1]
	v_pk_mul_f32 v[28:29], v[138:139], v[28:29] op_sel_hi:[0,1]
	v_pk_mul_f32 v[26:27], v[138:139], v[26:27] op_sel_hi:[0,1]
	v_pk_mul_f32 v[24:25], v[138:139], v[24:25] op_sel_hi:[0,1]
	v_pk_mul_f32 v[22:23], v[138:139], v[22:23] op_sel_hi:[0,1]
	v_pk_mul_f32 v[20:21], v[138:139], v[20:21] op_sel_hi:[0,1]
	v_pk_mul_f32 v[18:19], v[138:139], v[18:19] op_sel_hi:[0,1]
	v_pk_mul_f32 v[16:17], v[138:139], v[16:17] op_sel_hi:[0,1]
	v_pk_mul_f32 v[14:15], v[138:139], v[14:15] op_sel_hi:[0,1]
	v_pk_mul_f32 v[12:13], v[138:139], v[12:13] op_sel_hi:[0,1]
	v_pk_mul_f32 v[10:11], v[138:139], v[10:11] op_sel_hi:[0,1]
	v_pk_mul_f32 v[8:9], v[138:139], v[8:9] op_sel_hi:[0,1]
	v_pk_mul_f32 v[6:7], v[138:139], v[6:7] op_sel_hi:[0,1]
	v_pk_mul_f32 v[4:5], v[138:139], v[4:5] op_sel_hi:[0,1]
	v_pk_mul_f32 v[2:3], v[138:139], v[2:3] op_sel_hi:[0,1]
	v_mul_f32_e32 v140, v140, v138
	v_mov_b32_e32 v138, 1.0
	v_xor_b32_e32 v179, 0x80000000, v141
	v_mov_b32_e32 v232, v179
	v_mov_b32_e32 v233, v179
	v_mov_b32_e32 v234, v179
	v_mov_b32_e32 v235, v179
	v_mov_b32_e32 v236, v179
	v_mov_b32_e32 v237, v179
	v_mov_b32_e32 v238, v179
	v_mov_b32_e32 v239, v179
	v_mov_b32_e32 v240, v179
	v_mov_b32_e32 v241, v179
	v_mov_b32_e32 v242, v179
	v_mov_b32_e32 v243, v179
	v_mov_b32_e32 v244, v179
	v_mov_b32_e32 v245, v179
	v_mov_b32_e32 v246, v179
	v_mov_b32_e32 v247, v179
.Lmla_c0:
	ds_read_b128 v[152:155], v149
	ds_read_b128 v[156:159], v149 offset:32
	ds_read_b128 v[160:163], v149 offset:64
	ds_read_b128 v[164:167], v149 offset:96
	ds_read_b128 v[168:171], v149 offset:128
	ds_read_b128 v[172:175], v149 offset:160
	s_waitcnt lgkmcnt(5)
	v_mfma_f32_32x32x16_bf16 v[52:67], v[152:155], v[68:71], v[232:247]
	ds_read_b128 v[152:155], v149 offset:6656
	s_waitcnt lgkmcnt(5)
	v_mfma_f32_32x32x16_bf16 v[52:67], v[156:159], v[72:75], v[52:67]
	ds_read_b128 v[156:159], v149 offset:6688
	s_waitcnt lgkmcnt(5)
	v_mfma_f32_32x32x16_bf16 v[52:67], v[160:163], v[76:79], v[52:67]
	ds_read_b128 v[160:163], v149 offset:6720
	s_waitcnt lgkmcnt(5)
	v_mfma_f32_32x32x16_bf16 v[52:67], v[164:167], v[80:83], v[52:67]
	ds_read_b128 v[164:167], v149 offset:6752
	s_waitcnt lgkmcnt(5)
	v_mfma_f32_32x32x16_bf16 v[52:67], v[168:171], v[84:87], v[52:67]
	ds_read_b128 v[168:171], v149 offset:6784
	ds_read_b128 v[198:201], v150 offset:26624
	s_waitcnt lgkmcnt(6)
	v_mfma_f32_32x32x16_bf16 v[52:67], v[172:175], v[88:91], v[52:67]
	ds_read_b128 v[172:175], v149 offset:6816
	ds_read_b128 v[202:205], v150 offset:26656
	ds_read_b128 v[206:209], v150 offset:31232
	ds_read_b128 v[210:213], v150 offset:31264
	s_waitcnt lgkmcnt(9)
	v_mfma_f32_32x32x16_bf16 v[36:51], v[152:155], v[68:71], v[232:247]
	s_waitcnt lgkmcnt(8)
	v_mfma_f32_32x32x16_bf16 v[36:51], v[156:159], v[72:75], v[36:51]
	s_nop 3
	v_exp_f32_e32 v52, v52
	v_exp_f32_e32 v53, v53
	s_waitcnt lgkmcnt(7)
	v_mfma_f32_32x32x16_bf16 v[36:51], v[160:163], v[76:79], v[36:51]
	v_exp_f32_e32 v54, v54
	v_exp_f32_e32 v55, v55
	v_exp_f32_e32 v56, v56
	v_exp_f32_e32 v57, v57
	v_exp_f32_e32 v58, v58
	v_exp_f32_e32 v59, v59
	s_waitcnt lgkmcnt(6)
	v_mfma_f32_32x32x16_bf16 v[36:51], v[164:167], v[80:83], v[36:51]
	v_exp_f32_e32 v60, v60
	v_exp_f32_e32 v61, v61
	v_exp_f32_e32 v62, v62
	v_exp_f32_e32 v63, v63
	v_exp_f32_e32 v64, v64
	v_exp_f32_e32 v65, v65
	s_waitcnt lgkmcnt(5)
	v_mfma_f32_32x32x16_bf16 v[36:51], v[168:171], v[84:87], v[36:51]
	v_exp_f32_e32 v66, v66
	v_exp_f32_e32 v67, v67
	v_add_f32_e32 v176, v52, v53
	v_add_f32_e32 v176, v54, v176
	v_add_f32_e32 v176, v55, v176
	v_add_f32_e32 v176, v56, v176
	v_add_f32_e32 v176, v57, v176
	v_add_f32_e32 v176, v58, v176
	v_add_f32_e32 v176, v59, v176
	s_waitcnt lgkmcnt(3)
	v_mfma_f32_32x32x16_bf16 v[36:51], v[172:175], v[88:91], v[36:51]
	v_add_f32_e32 v176, v60, v176
	v_add_f32_e32 v176, v61, v176
	v_add_f32_e32 v176, v62, v176
	v_add_f32_e32 v176, v63, v176
	v_add_f32_e32 v176, v64, v176
	v_add_f32_e32 v176, v65, v176
	v_add_f32_e32 v176, v66, v176
	v_add_f32_e32 v176, v67, v176
	v_cvt_pk_bf16_f32 v214, v52, v53
	v_cvt_pk_bf16_f32 v215, v54, v55
	v_cvt_pk_bf16_f32 v216, v56, v57
	v_cvt_pk_bf16_f32 v217, v58, v59
	v_cvt_pk_bf16_f32 v218, v60, v61
	v_cvt_pk_bf16_f32 v219, v62, v63
	v_cvt_pk_bf16_f32 v220, v64, v65
	v_cvt_pk_bf16_f32 v221, v66, v67
	v_mfma_f32_32x32x16_bf16 v[2:17], v[198:201], v[214:217], v[2:17]
	ds_read_b128 v[198:201], v150 offset:26688
	s_waitcnt lgkmcnt(2)
; #define M2_STORE(S, buf) { M2_SK(0, S##k0, buf) M2_SK(1, S##k1, buf) M2_SK(2, S##k2, buf) M2_SV(0, S##v0, buf) M2_SV(1, S##v1, buf) }
; DI void flash_mla2(const bf16_t* __restrict__ Qp, const bf16_t* __restrict__ Kp, const bf16_t* __restrict__ Vtp,
;                    bf16_t* __restrict__ Op, char* smem, float& ssq) {
;     ...
;         M2_STORE(a, 0);
;         __syncthreads();
;         M2_LOAD(a, min(kt + 2, NKT - 1));
;         M2_COMPUTE(0);
;         M2_STORE(b, 1);
;         __syncthreads();
;         M2_LOAD(b, min(kt + 3, NKT - 1));
;         M2_COMPUTE(1);
	v_mfma_f32_32x32x16_bf16 v[18:33], v[206:209], v[214:217], v[18:33]
	ds_read_b128 v[206:209], v150 offset:31296
	v_exp_f32_e32 v36, v36
	v_exp_f32_e32 v37, v37
	v_exp_f32_e32 v38, v38
	v_exp_f32_e32 v39, v39
	v_exp_f32_e32 v40, v40
	v_exp_f32_e32 v41, v41
	v_mfma_f32_32x32x16_bf16 v[2:17], v[202:205], v[218:221], v[2:17]
	ds_read_b128 v[202:205], v150 offset:26720
	v_exp_f32_e32 v42, v42
	v_exp_f32_e32 v43, v43
	v_exp_f32_e32 v44, v44
	v_exp_f32_e32 v45, v45
	v_exp_f32_e32 v46, v46
	v_exp_f32_e32 v47, v47
	s_waitcnt lgkmcnt(3)
	v_mfma_f32_32x32x16_bf16 v[18:33], v[210:213], v[218:221], v[18:33]
	ds_read_b128 v[210:213], v150 offset:31328
	v_exp_f32_e32 v48, v48
	v_exp_f32_e32 v49, v49
	v_exp_f32_e32 v50, v50
	v_exp_f32_e32 v51, v51
	v_cvt_pk_bf16_f32 v222, v36, v37
	v_cvt_pk_bf16_f32 v223, v38, v39
	v_cvt_pk_bf16_f32 v224, v40, v41
	v_cvt_pk_bf16_f32 v225, v42, v43
	v_add_f32_e32 v177, v36, v37
	v_add_f32_e32 v177, v38, v177
	s_waitcnt lgkmcnt(3)
	v_mfma_f32_32x32x16_bf16 v[2:17], v[198:201], v[222:225], v[2:17]
	v_add_f32_e32 v177, v39, v177
	v_add_f32_e32 v177, v40, v177
	v_add_f32_e32 v177, v41, v177
	v_add_f32_e32 v177, v42, v177
	v_add_f32_e32 v177, v43, v177
	v_add_f32_e32 v177, v44, v177
	s_waitcnt lgkmcnt(2)
	v_mfma_f32_32x32x16_bf16 v[18:33], v[206:209], v[222:225], v[18:33]
	v_add_f32_e32 v177, v45, v177
	v_add_f32_e32 v177, v46, v177
	v_add_f32_e32 v177, v47, v177
	v_add_f32_e32 v177, v48, v177
	v_add_f32_e32 v177, v49, v177
	v_add_f32_e32 v177, v50, v177
	v_add_f32_e32 v177, v51, v177
	v_cvt_pk_bf16_f32 v226, v44, v45
	v_cvt_pk_bf16_f32 v227, v46, v47
	v_cvt_pk_bf16_f32 v228, v48, v49
	v_cvt_pk_bf16_f32 v229, v50, v51
	v_add_f32_e32 v176, v176, v177
	s_waitcnt lgkmcnt(1)
	v_mfma_f32_32x32x16_bf16 v[2:17], v[202:205], v[226:229], v[2:17]
	v_add_f32_e32 v140, v140, v176
	s_waitcnt lgkmcnt(0)
	v_mfma_f32_32x32x16_bf16 v[18:33], v[210:213], v[226:229], v[18:33]
	v_cmp_lt_f32_e32 vcc, 0x46000000, v176
	s_cbranch_vccz .Lmla_f0
	ds_bpermute_b32 v180, v143, v176
	s_waitcnt lgkmcnt(0)
	v_add_f32_e32 v180, v176, v180
	v_frexp_exp_i32_f32_e32 v178, v180
	v_cmp_lt_f32_e32 vcc, 0x46800000, v180
	v_cvt_f32_i32_e32 v178, v178
	s_nop 0
	v_cndmask_b32_e32 v181, 0, v178, vcc
	v_add_f32_e32 v141, v141, v181
	v_exp_f32_e64 v138, -v181
.Lmla_f0:
	s_add_i32 s36, s35, 4
	s_min_u32 s41, s36, 0x7f
	s_mul_i32 s36, s41, 0x3000
	s_add_u32 s36, s16, s36
	s_addc_u32 s37, s17, 0
	s_waitcnt lgkmcnt(0)
	s_barrier
	s_waitcnt vmcnt(9)
	ds_write_b128 v144, v[92:95]
	s_waitcnt vmcnt(8)
	ds_write_b128 v145, v[100:103]
	s_waitcnt vmcnt(6)
	ds_write_b128 v146, v[96:99]
	ds_write_b128 v147, v[104:107] offset:26624
	s_waitcnt vmcnt(5)
	ds_write_b128 v148, v[108:111] offset:26624
	global_load_dwordx4 v[92:95], v136, s[36:37]
	global_load_dwordx4 v[100:103], v137, s[36:37] offset:-4096
	global_load_dwordx4 v[96:99], v137, s[36:37]
	s_lshl_b32 s36, s41, 13
	s_add_u32 s36, s18, s36
	s_addc_u32 s37, s19, 0
	s_add_u32 s36, s36, 0x800
	s_addc_u32 s37, s37, 0
	global_load_dwordx4 v[104:107], v151, s[36:37] offset:-2048
	global_load_dwordx4 v[108:111], v151, s[36:37] offset:2048
	v_cmp_neq_f32_e32 vcc, 1.0, v138
	s_cbranch_vccz .Lmla_c1
	v_pk_mul_f32 v[32:33], v[138:139], v[32:33] op_sel_hi:[0,1]
	v_pk_mul_f32 v[30:31], v[138:139], v[30:31] op_sel_hi:[0,1]
	v_pk_mul_f32 v[28:29], v[138:139], v[28:29] op_sel_hi:[0,1]
	v_pk_mul_f32 v[26:27], v[138:139], v[26:27] op_sel_hi:[0,1]
	v_pk_mul_f32 v[24:25], v[138:139], v[24:25] op_sel_hi:[0,1]
	v_pk_mul_f32 v[22:23], v[138:139], v[22:23] op_sel_hi:[0,1]
	v_pk_mul_f32 v[20:21], v[138:139], v[20:21] op_sel_hi:[0,1]
	v_pk_mul_f32 v[18:19], v[138:139], v[18:19] op_sel_hi:[0,1]
	v_pk_mul_f32 v[16:17], v[138:139], v[16:17] op_sel_hi:[0,1]
	v_pk_mul_f32 v[14:15], v[138:139], v[14:15] op_sel_hi:[0,1]
	v_pk_mul_f32 v[12:13], v[138:139], v[12:13] op_sel_hi:[0,1]
	v_pk_mul_f32 v[10:11], v[138:139], v[10:11] op_sel_hi:[0,1]
	v_pk_mul_f32 v[8:9], v[138:139], v[8:9] op_sel_hi:[0,1]
	v_pk_mul_f32 v[6:7], v[138:139], v[6:7] op_sel_hi:[0,1]
	v_pk_mul_f32 v[4:5], v[138:139], v[4:5] op_sel_hi:[0,1]
	v_pk_mul_f32 v[2:3], v[138:139], v[2:3] op_sel_hi:[0,1]
	v_mul_f32_e32 v140, v140, v138
	v_mov_b32_e32 v138, 1.0
	v_xor_b32_e32 v179, 0x80000000, v141
	v_mov_b32_e32 v232, v179
	v_mov_b32_e32 v233, v179
	v_mov_b32_e32 v234, v179
	v_mov_b32_e32 v235, v179
	v_mov_b32_e32 v236, v179
	v_mov_b32_e32 v237, v179
	v_mov_b32_e32 v238, v179
	v_mov_b32_e32 v239, v179
	v_mov_b32_e32 v240, v179
	v_mov_b32_e32 v241, v179
	v_mov_b32_e32 v242, v179
	v_mov_b32_e32 v243, v179
	v_mov_b32_e32 v244, v179
	v_mov_b32_e32 v245, v179
	v_mov_b32_e32 v246, v179
	v_mov_b32_e32 v247, v179
; #define M2_STORE(S, buf) { M2_SK(0, S##k0, buf) M2_SK(1, S##k1, buf) M2_SK(2, S##k2, buf) M2_SV(0, S##v0, buf) M2_SV(1, S##v1, buf) }
; DI void flash_mla2(const bf16_t* __restrict__ Qp, const bf16_t* __restrict__ Kp, const bf16_t* __restrict__ Vtp,
;                    bf16_t* __restrict__ Op, char* smem, float& ssq) {
;     ...
;         M2_STORE(b, 1);
;         __syncthreads();
;         M2_LOAD(b, min(kt + 3, NKT - 1));
;         M2_COMPUTE(1);
;     }
.Lmla_c1:
	ds_read_b128 v[152:155], v149 offset:13312
	ds_read_b128 v[156:159], v149 offset:13344
	ds_read_b128 v[160:163], v149 offset:13376
	ds_read_b128 v[164:167], v149 offset:13408
	ds_read_b128 v[168:171], v149 offset:13440
	ds_read_b128 v[172:175], v149 offset:13472
	s_waitcnt lgkmcnt(5)
	v_mfma_f32_32x32x16_bf16 v[52:67], v[152:155], v[68:71], v[232:247]
	ds_read_b128 v[152:155], v149 offset:19968
	s_waitcnt lgkmcnt(5)
	v_mfma_f32_32x32x16_bf16 v[52:67], v[156:159], v[72:75], v[52:67]
	ds_read_b128 v[156:159], v149 offset:20000
	s_waitcnt lgkmcnt(5)
	v_mfma_f32_32x32x16_bf16 v[52:67], v[160:163], v[76:79], v[52:67]
	ds_read_b128 v[160:163], v149 offset:20032
	s_waitcnt lgkmcnt(5)
	v_mfma_f32_32x32x16_bf16 v[52:67], v[164:167], v[80:83], v[52:67]
	ds_read_b128 v[164:167], v149 offset:20064
	s_waitcnt lgkmcnt(5)
	v_mfma_f32_32x32x16_bf16 v[52:67], v[168:171], v[84:87], v[52:67]
	ds_read_b128 v[168:171], v149 offset:20096
	ds_read_b128 v[198:201], v150 offset:35840
	s_waitcnt lgkmcnt(6)
	v_mfma_f32_32x32x16_bf16 v[52:67], v[172:175], v[88:91], v[52:67]
	ds_read_b128 v[172:175], v149 offset:20128
	ds_read_b128 v[202:205], v150 offset:35872
	ds_read_b128 v[206:209], v150 offset:40448
	ds_read_b128 v[210:213], v150 offset:40480
	s_waitcnt lgkmcnt(9)
	v_mfma_f32_32x32x16_bf16 v[36:51], v[152:155], v[68:71], v[232:247]
	s_waitcnt lgkmcnt(8)
	v_mfma_f32_32x32x16_bf16 v[36:51], v[156:159], v[72:75], v[36:51]
	s_nop 3
	v_exp_f32_e32 v52, v52
	v_exp_f32_e32 v53, v53
	s_waitcnt lgkmcnt(7)
	v_mfma_f32_32x32x16_bf16 v[36:51], v[160:163], v[76:79], v[36:51]
	v_exp_f32_e32 v54, v54
	v_exp_f32_e32 v55, v55
	v_exp_f32_e32 v56, v56
	v_exp_f32_e32 v57, v57
	v_exp_f32_e32 v58, v58
	v_exp_f32_e32 v59, v59
	s_waitcnt lgkmcnt(6)
	v_mfma_f32_32x32x16_bf16 v[36:51], v[164:167], v[80:83], v[36:51]
	v_exp_f32_e32 v60, v60
	v_exp_f32_e32 v61, v61
	v_exp_f32_e32 v62, v62
	v_exp_f32_e32 v63, v63
	v_exp_f32_e32 v64, v64
	v_exp_f32_e32 v65, v65
	s_waitcnt lgkmcnt(5)
	v_mfma_f32_32x32x16_bf16 v[36:51], v[168:171], v[84:87], v[36:51]
	v_exp_f32_e32 v66, v66
	v_exp_f32_e32 v67, v67
	v_add_f32_e32 v176, v52, v53
	v_add_f32_e32 v176, v54, v176
	v_add_f32_e32 v176, v55, v176
	v_add_f32_e32 v176, v56, v176
	v_add_f32_e32 v176, v57, v176
	v_add_f32_e32 v176, v58, v176
	v_add_f32_e32 v176, v59, v176
	s_waitcnt lgkmcnt(3)
	v_mfma_f32_32x32x16_bf16 v[36:51], v[172:175], v[88:91], v[36:51]
	v_add_f32_e32 v176, v60, v176
	v_add_f32_e32 v176, v61, v176
	v_add_f32_e32 v176, v62, v176
	v_add_f32_e32 v176, v63, v176
	v_add_f32_e32 v176, v64, v176
	v_add_f32_e32 v176, v65, v176
	v_add_f32_e32 v176, v66, v176
	v_add_f32_e32 v176, v67, v176
	v_cvt_pk_bf16_f32 v214, v52, v53
	v_cvt_pk_bf16_f32 v215, v54, v55
	v_cvt_pk_bf16_f32 v216, v56, v57
	v_cvt_pk_bf16_f32 v217, v58, v59
	v_cvt_pk_bf16_f32 v218, v60, v61
	v_cvt_pk_bf16_f32 v219, v62, v63
	v_cvt_pk_bf16_f32 v220, v64, v65
	v_cvt_pk_bf16_f32 v221, v66, v67
	v_mfma_f32_32x32x16_bf16 v[2:17], v[198:201], v[214:217], v[2:17]
	ds_read_b128 v[198:201], v150 offset:35904
	s_waitcnt lgkmcnt(2)
	v_mfma_f32_32x32x16_bf16 v[18:33], v[206:209], v[214:217], v[18:33]
	ds_read_b128 v[206:209], v150 offset:40512
	v_exp_f32_e32 v36, v36
	v_exp_f32_e32 v37, v37
	v_exp_f32_e32 v38, v38
	v_exp_f32_e32 v39, v39
	v_exp_f32_e32 v40, v40
	v_exp_f32_e32 v41, v41
	v_mfma_f32_32x32x16_bf16 v[2:17], v[202:205], v[218:221], v[2:17]
	ds_read_b128 v[202:205], v150 offset:35936
	v_exp_f32_e32 v42, v42
	v_exp_f32_e32 v43, v43
	v_exp_f32_e32 v44, v44
	v_exp_f32_e32 v45, v45
	v_exp_f32_e32 v46, v46
	v_exp_f32_e32 v47, v47
	s_waitcnt lgkmcnt(3)
	v_mfma_f32_32x32x16_bf16 v[18:33], v[210:213], v[218:221], v[18:33]
	ds_read_b128 v[210:213], v150 offset:40544
	v_exp_f32_e32 v48, v48
	v_exp_f32_e32 v49, v49
	v_exp_f32_e32 v50, v50
	v_exp_f32_e32 v51, v51
	v_cvt_pk_bf16_f32 v222, v36, v37
	v_cvt_pk_bf16_f32 v223, v38, v39
	v_cvt_pk_bf16_f32 v224, v40, v41
	v_cvt_pk_bf16_f32 v225, v42, v43
	v_add_f32_e32 v177, v36, v37
	v_add_f32_e32 v177, v38, v177
	s_waitcnt lgkmcnt(3)
	v_mfma_f32_32x32x16_bf16 v[2:17], v[198:201], v[222:225], v[2:17]
	v_add_f32_e32 v177, v39, v177
	v_add_f32_e32 v177, v40, v177
	v_add_f32_e32 v177, v41, v177
	v_add_f32_e32 v177, v42, v177
	v_add_f32_e32 v177, v43, v177
	v_add_f32_e32 v177, v44, v177
	s_waitcnt lgkmcnt(2)
	v_mfma_f32_32x32x16_bf16 v[18:33], v[206:209], v[222:225], v[18:33]
	v_add_f32_e32 v177, v45, v177
	v_add_f32_e32 v177, v46, v177
	v_add_f32_e32 v177, v47, v177
	v_add_f32_e32 v177, v48, v177
	v_add_f32_e32 v177, v49, v177
	v_add_f32_e32 v177, v50, v177
	v_add_f32_e32 v177, v51, v177
	v_cvt_pk_bf16_f32 v226, v44, v45
	v_cvt_pk_bf16_f32 v227, v46, v47
	v_cvt_pk_bf16_f32 v228, v48, v49
	v_cvt_pk_bf16_f32 v229, v50, v51
	v_add_f32_e32 v176, v176, v177
	s_waitcnt lgkmcnt(1)
	v_mfma_f32_32x32x16_bf16 v[2:17], v[202:205], v[226:229], v[2:17]
	v_add_f32_e32 v140, v140, v176
	s_waitcnt lgkmcnt(0)
	v_mfma_f32_32x32x16_bf16 v[18:33], v[210:213], v[226:229], v[18:33]
	v_cmp_lt_f32_e32 vcc, 0x46000000, v176
	s_cbranch_vccz .Lmla_f1
	ds_bpermute_b32 v180, v143, v176
	s_waitcnt lgkmcnt(0)
	v_add_f32_e32 v180, v176, v180
	v_frexp_exp_i32_f32_e32 v178, v180
	v_cmp_lt_f32_e32 vcc, 0x46800000, v180
	v_cvt_f32_i32_e32 v178, v178
	s_nop 0
	v_cndmask_b32_e32 v181, 0, v178, vcc
	v_add_f32_e32 v141, v141, v181
	v_exp_f32_e64 v138, -v181
.Lmla_f1:
	s_cmpk_lt_u32 s35, 0x7e
	s_cbranch_scc1 .LBB0_184
	s_branch .LBB0_181
